# sliding-window attention key loop: K/V LDS tiles double-buffered too (one barrier per key tile)
# speedup vs baseline: 1.0042x; 1.0008x over previous
; DI void win_attn_item(const Params& P, int it, u16* sQ, u16* sKunused, u16* sVunused) {
;     ...
;   const int t0 = tbk * 32;
; #pragma unroll
;   for (int i = 0; i < 4; ++i) {
;     const int c = tid + 256 * i, row = c >> 3, ch = c & 7;
;     *(uint4*)(sQ + row * 72 + ch * 8) = *(const uint4*)(QR + (tb + t0 + (row & 31)) * 256 + (row >> 5) * 64 + ch * 8);
;   }
;   __syncthreads();
;   bf16x8 bq[2][2];
;   int tq[2];
; #pragma unroll
;   for (int qt = 0; qt < 2; ++qt) {
;     const int rowq = 32 * w + 16 * qt + r16;
;     bq[qt][0] = *(const bf16x8*)(sQ + rowq * 72 + quad * 8);
;     bq[qt][1] = *(const bf16x8*)(sQ + rowq * 72 + 32 + quad * 8);
;     tq[qt] = t0 + 16 * qt + r16;
;   }
;   f32x4 ot[2][4];
; #pragma unroll
;   for (int qt = 0; qt < 2; ++qt)
; #pragma unroll
;     for (int dt = 0; dt < 4; ++dt) ot[qt][dt] = (f32x4){0.f, 0.f, 0.f, 0.f};
;   float m[2] = {-1e30f, -1e30f}, lsum[2] = {0.f, 0.f};
;   const int lo = (t0 - 511) > 0 ? (t0 - 511) : 0;
;   const int kb_lo = lo >> 6, kb_hi = (t0 + 31) >> 6;
;   uint4 pk0, pk1, pv0, pv1;
;   kv_gload(pk0, pk1, pv0, pv1, PROJ + (tb + kb_lo * 64) * PW + P_KV + 256, PROJ + (tb + kb_lo * 64) * PW + P_KV + 320, PW);
;   for (int kb = kb_lo; kb <= kb_hi; ++kb) {
;     __syncthreads();
;     kv_store(pk0, pk1, pv0, pv1, sK, sVt);
;     __syncthreads();
;     if (kb < kb_hi) kv_gload(pk0, pk1, pv0, pv1, PROJ + (tb + (kb + 1) * 64) * PW + P_KV + 256, PROJ + (tb + (kb + 1) * 64) * PW + P_KV + 320, PW);
.LBB0_442:
	s_andn2_b64 vcc, exec, s[0:1]
	s_cbranch_vccnz .LBB0_461
	v_mov_b32_e32 v167, v160
	s_mov_b64 s[0:1], 0
	s_mov_b64 s[2:3], 0
	s_add_i32 s6, s40, 0xfffff780
	s_add_u32 s2, s70, s2
	s_addc_u32 s3, s71, s3
	s_add_u32 s4, s2, 0x18000000
	s_addc_u32 s5, s3, 0
	s_lshl_b32 s7, s6, 12
	s_not_b32 s6, s6
	s_lshl_b32 s6, s6, 2
	s_and_b32 s42, s6, 0xfe0
	v_lshlrev_b32_e32 v0, 4, v167
	v_ashrrev_i32_e32 v21, 3, v167
	s_and_b32 s41, s7, 0x7000
	v_and_b32_e32 v2, 0x70, v0
	v_and_or_b32 v0, v21, 31, s42
	v_or_b32_e32 v0, s41, v0
	v_ashrrev_i32_e32 v3, 2, v167
	v_lshlrev_b32_e32 v162, 9, v0
	v_and_b32_e32 v4, 0xffffffc0, v3
	v_add_u32_e32 v6, 0x100, v167
	v_lshl_add_u64 v[0:1], s[4:5], 0, v[162:163]
	v_ashrrev_i32_e32 v5, 31, v4
	v_ashrrev_i32_e32 v24, 3, v6
	v_lshl_add_u64 v[0:1], v[4:5], 1, v[0:1]
	v_and_or_b32 v4, v24, 31, s42
	v_or_b32_e32 v4, s41, v4
	v_ashrrev_i32_e32 v6, 2, v6
	v_lshlrev_b32_e32 v162, 9, v4
	v_and_b32_e32 v6, 0xffffffc0, v6
	v_lshl_add_u64 v[4:5], s[4:5], 0, v[162:163]
	v_ashrrev_i32_e32 v7, 31, v6
	v_mov_b32_e32 v3, v163
	v_lshl_add_u64 v[4:5], v[6:7], 1, v[4:5]
	s_waitcnt vmcnt(4)
	v_add_u32_e32 v12, 0x200, v167
	s_mov_b64 s[2:3], 0
	v_lshl_add_u64 v[0:1], v[0:1], 0, v[2:3]
	v_lshl_add_u64 v[8:9], v[4:5], 0, v[2:3]
	v_ashrrev_i32_e32 v26, 3, v12
	global_load_dwordx4 v[4:7], v[0:1], off
	s_nop 0
	global_load_dwordx4 v[8:11], v[8:9], off
	v_and_or_b32 v0, v26, 31, s42
	v_or_b32_e32 v0, s41, v0
	v_ashrrev_i32_e32 v12, 2, v12
	v_lshlrev_b32_e32 v162, 9, v0
	v_and_b32_e32 v12, 0xffffffc0, v12
	v_add_u32_e32 v14, 0x300, v167
	v_lshl_add_u64 v[0:1], s[4:5], 0, v[162:163]
	v_ashrrev_i32_e32 v13, 31, v12
	v_ashrrev_i32_e32 v28, 3, v14
	v_lshl_add_u64 v[0:1], v[12:13], 1, v[0:1]
	v_and_or_b32 v12, v28, 31, s42
	v_or_b32_e32 v12, s41, v12
	v_ashrrev_i32_e32 v14, 2, v14
	v_lshlrev_b32_e32 v162, 9, v12
	v_and_b32_e32 v14, 0xffffffc0, v14
	v_lshl_add_u64 v[12:13], s[4:5], 0, v[162:163]
	v_ashrrev_i32_e32 v15, 31, v14
	v_lshl_add_u64 v[12:13], v[14:15], 1, v[12:13]
	v_lshl_add_u64 v[0:1], v[0:1], 0, v[2:3]
	v_lshl_add_u64 v[16:17], v[12:13], 0, v[2:3]
	global_load_dwordx4 v[12:15], v[0:1], off
	s_nop 0
	global_load_dwordx4 v[16:19], v[16:17], off
	v_and_b32_e32 v168, 15, v167
	v_lshrrev_b32_e32 v1, 1, v167
	s_mov_b32 s4, 0xfffffe0
	v_and_b32_e32 v20, 48, v167
	v_and_or_b32 v30, v1, s4, v168
	v_mad_u64_u32 v[22:23], s[4:5], v21, s54, v[2:3]
	v_mad_u64_u32 v[20:21], s[4:5], v30, s54, v[20:21]
	v_mad_u64_u32 v[24:25], s[4:5], v24, s54, v[2:3]
	v_mad_u64_u32 v[26:27], s[4:5], v26, s54, v[2:3]
	v_mad_u64_u32 v[28:29], s[4:5], v28, s54, v[2:3]
	v_sub_u32_e64 v2, s42, v191 clamp
	v_bfe_u32 v0, v167, 4, 2
	v_readfirstlane_b32 s4, v2
	s_bfe_u32 s43, s6, 0x60006
	s_lshr_b32 s44, s4, 6
	v_mov_b32_e32 v3, v160
	s_mov_b64 s[4:5], -1
	s_cmp_le_u32 s44, s43
	v_lshlrev_b32_e32 v169, 2, v0
	s_waitcnt vmcnt(3)
	ds_write_b128 v22, v[4:7]
	s_waitcnt vmcnt(2)
	ds_write_b128 v24, v[8:11]
	s_waitcnt vmcnt(1)
	ds_write_b128 v26, v[12:15]
	s_waitcnt vmcnt(0)
	ds_write_b128 v28, v[16:19]
	s_waitcnt lgkmcnt(0)
	s_barrier
	ds_read_b128 v[48:51], v20
	ds_read_b128 v[52:55], v20 offset:64
	ds_read_b128 v[56:59], v20 offset:2304
	ds_read_b128 v[60:63], v20 offset:2368
	s_cbranch_scc0 .LBB0_458
	s_add_u32 s0, s70, s0
	s_addc_u32 s1, s71, s1
	v_and_b32_e32 v2, 0xfc0, v2
	s_add_u32 s36, s0, 0x4000000
	v_or_b32_e32 v2, s41, v2
	s_movk_i32 s4, 0x1600
	s_addc_u32 s37, s1, 0
	v_mul_lo_u32 v162, v2, s4
	v_ashrrev_i32_e32 v8, 3, v3
	v_lshl_add_u64 v[4:5], s[36:37], 0, v[162:163]
	v_add_u32_e32 v2, 32, v8
	v_mad_i64_i32 v[6:7], s[0:1], v2, s4, v[4:5]
	v_lshlrev_b32_e32 v2, 4, v3
	v_and_b32_e32 v162, 0x70, v2
	v_lshl_add_u64 v[2:3], v[6:7], 0, v[162:163]
	v_mad_i64_i32 v[4:5], s[0:1], v8, s4, v[4:5]
	v_lshl_add_u64 v[4:5], v[4:5], 0, v[162:163]
	global_load_dwordx4 v[64:67], v[2:3], off offset:1152
	global_load_dwordx4 v[76:79], v[2:3], off offset:1024
	global_load_dwordx4 v[72:75], v[4:5], off offset:1152
	global_load_dwordx4 v[68:71], v[4:5], off offset:1024
	v_and_b32_e32 v2, 63, v167
	s_sub_i32 s0, s42, 17
	v_or_b32_e32 v2, 48, v2
	v_lshlrev_b32_e32 v166, 2, v0
	v_add_u32_e32 v0, s0, v168
	v_and_b32_e32 v1, 24, v1
	v_mul_u32_u24_e32 v4, 0x48, v168
	v_mul_u32_u24_e32 v2, 0x48, v2
	v_sub_u32_e32 v0, v0, v166
	s_lshl_b32 s0, s44, 6
	v_lshlrev_b32_e32 v3, 1, v1
	v_lshlrev_b32_e32 v4, 1, v4
	v_lshlrev_b32_e32 v2, 1, v2
	v_subrev_u32_e32 v174, s0, v0
	v_subrev_u32_e32 v0, s42, v166
	v_mov_b32_e32 v176, 0
	v_add_u32_e32 v170, v3, v4
	v_add_u32_e32 v171, v3, v2
	v_add_u32_e32 v172, v4, v1
	v_add_u32_e32 v173, v2, v1
	v_mov_b32_e32 v249, v170
	v_mov_b32_e32 v250, v171
	v_mov_b32_e32 v251, v172
	v_mov_b32_e32 v252, v173
	v_mov_b32_e32 v253, 0x4800
	s_or_b32 s45, s42, 16
	s_add_i32 s46, s42, 0xfffffe0f
	s_add_i32 s48, s42, 0xfffffe1f
	v_sub_u32_e32 v175, v0, v168
	s_or_b32 s49, s0, 63
	v_mov_b32_e32 v177, 0xf149f2ca
	v_mov_b32_e32 v180, 0xf149f2ca
	v_mov_b32_e32 v178, 0
	v_mov_b32_e32 v16, 0
	v_mov_b32_e32 v17, v176
	v_mov_b32_e32 v18, v176
	v_mov_b32_e32 v19, v176
	v_mov_b32_e32 v20, 0
	v_mov_b32_e32 v21, v176
	v_mov_b32_e32 v22, v176
	v_mov_b32_e32 v23, v176
	v_mov_b32_e32 v24, 0
	v_mov_b32_e32 v25, v176
	v_mov_b32_e32 v26, v176
	v_mov_b32_e32 v27, v176
	v_mov_b32_e32 v28, 0
	v_mov_b32_e32 v29, v176
	v_mov_b32_e32 v30, v176
	v_mov_b32_e32 v31, v176
	v_mov_b32_e32 v32, 0
	v_mov_b32_e32 v33, v176
	v_mov_b32_e32 v34, v176
	v_mov_b32_e32 v35, v176
	v_mov_b32_e32 v36, 0
	v_mov_b32_e32 v37, v176
	v_mov_b32_e32 v38, v176
	v_mov_b32_e32 v39, v176
	v_mov_b32_e32 v40, 0
	v_mov_b32_e32 v41, v176
	v_mov_b32_e32 v42, v176
	v_mov_b32_e32 v43, v176
	v_mov_b32_e32 v44, 0
	v_mov_b32_e32 v45, v176
	v_mov_b32_e32 v46, v176
	v_mov_b32_e32 v47, v176
; DI int TID() { int t = threadIdx.x; asm volatile("" : "+v"(t)); return t; }
; DI void kv_store(const uint4& k0, const uint4& k1, const uint4& v0, const uint4& v1, u16* sK, u16* sVt) {
;   const int tid = TID(), r0 = tid >> 3, ch = tid & 7;
;   *(uint4*)(sK + r0 * 72 + ch * 8) = k0; *(uint4*)(sK + (r0 + 32) * 72 + ch * 8) = k1;
;   const int ksw = 16 * (ch >> 1);
;   st_kt(sVt, ch * 8, r0 ^ ksw, v0); st_kt(sVt, ch * 8, (r0 + 32) ^ ksw, v1);
; }
; DI void win_attn_item(const Params& P, int it, u16* sQ, u16* sKunused, u16* sVunused) {
;     ...
;   for (int kb = kb_lo; kb <= kb_hi; ++kb) {
;     __syncthreads();
;     kv_store(pk0, pk1, pv0, pv1, sK, sVt);
;     __syncthreads();
;     if (kb < kb_hi) kv_gload(pk0, pk1, pv0, pv1, PROJ + (tb + (kb + 1) * 64) * PW + P_KV + 256, PROJ + (tb + (kb + 1) * 64) * PW + P_KV + 320, PW);
.LBB0_445:
	v_mov_b32_e32 v0, v160
	s_waitcnt lgkmcnt(0)
	v_xor_b32_e32 v253, 0x4800, v253
	v_add_u32_e32 v170, v253, v249
	v_add_u32_e32 v171, v253, v250
	v_add_u32_e32 v172, v253, v251
	v_add_u32_e32 v173, v253, v252
	s_cmp_ge_u32 s44, s43
	v_ashrrev_i32_e32 v1, 3, v0
	v_lshlrev_b32_e32 v0, 3, v0
	v_add_u32_e32 v4, 32, v1
	v_mul_lo_u32 v2, v1, s54
	v_and_b32_e32 v3, 56, v0
	v_bitop3_b32 v1, v0, v1, 48 bitop3:0x6c
	v_bitop3_b32 v0, v4, v0, 48 bitop3:0x78
	v_lshlrev_b32_e32 v1, 1, v1
	v_lshlrev_b32_e32 v0, 1, v0
	s_cselect_b64 s[38:39], -1, 0
	v_lshl_add_u32 v2, v3, 1, v2
	v_mad_u32_u24 v1, v3, s54, v1
	v_mad_u32_u24 v0, v3, s54, v0
	v_add_u32_e32 v2, v253, v2
	v_add_u32_e32 v1, v253, v1
	v_add_u32_e32 v0, v253, v0
	s_and_b64 vcc, exec, s[38:39]
	s_waitcnt vmcnt(0)
	ds_write_b128 v2, v[68:71] offset:18432
	ds_write_b128 v2, v[76:79] offset:23040
	ds_write_b16 v1, v72 offset:27648
	ds_write_b16_d16_hi v1, v72 offset:27792
	ds_write_b16 v1, v73 offset:27936
	ds_write_b16_d16_hi v1, v73 offset:28080
	ds_write_b16 v1, v74 offset:28224
	ds_write_b16_d16_hi v1, v74 offset:28368
	ds_write_b16 v1, v75 offset:28512
	ds_write_b16_d16_hi v1, v75 offset:28656
	ds_write_b16 v0, v64 offset:27648
	ds_write_b16_d16_hi v0, v64 offset:27792
	ds_write_b16 v0, v65 offset:27936
	ds_write_b16_d16_hi v0, v65 offset:28080
	ds_write_b16 v0, v66 offset:28224
	ds_write_b16_d16_hi v0, v66 offset:28368
	ds_write_b16 v0, v67 offset:28512
	ds_write_b16_d16_hi v0, v67 offset:28656
	s_waitcnt lgkmcnt(0)
	s_barrier
	s_cbranch_vccnz .LBB0_447
	s_add_i32 s0, s41, s49
	s_add_i32 s0, s0, 1
	s_mul_hi_u32 s1, s0, 0x1600
	s_mulk_i32 s0, 0x1600
	s_add_u32 s0, s36, s0
	v_mov_b32_e32 v4, v160
	s_addc_u32 s1, s37, s1
	v_mov_b64_e32 v[0:1], s[0:1]
	v_ashrrev_i32_e32 v5, 3, v4
	s_movk_i32 s4, 0x1600
	v_lshlrev_b32_e32 v4, 4, v4
	v_mad_i64_i32 v[2:3], s[0:1], v5, s4, v[0:1]
	v_and_b32_e32 v162, 0x70, v4
	v_add_u32_e32 v4, 32, v5
	v_lshl_add_u64 v[2:3], v[2:3], 0, v[162:163]
	v_mad_i64_i32 v[0:1], s[0:1], v4, s4, v[0:1]
	v_lshl_add_u64 v[0:1], v[0:1], 0, v[162:163]
	global_load_dwordx4 v[68:71], v[2:3], off offset:1024
	global_load_dwordx4 v[72:75], v[2:3], off offset:1152
	global_load_dwordx4 v[76:79], v[0:1], off offset:1024
	global_load_dwordx4 v[64:67], v[0:1], off offset:1152
